# grid barrier: the per-XCD generation bump (no longer read by anyone) removed from the leader path
# speedup vs baseline: 1.0073x; 1.0073x over previous
.LBB0_418:
	s_or_b64 exec, exec, s[4:5]
	s_mov_b64 s[4:5], exec
	v_mbcnt_lo_u32_b32 v0, s4, 0
	v_mbcnt_hi_u32_b32 v0, s5, v0
	v_cmp_eq_u32_e32 vcc, 0, v0
	s_waitcnt vmcnt(0)
	buffer_inv sc1
	s_and_saveexec_b64 s[8:9], vcc
	s_cbranch_execz .LBB0_420
	s_bcnt1_i32_b64 s4, s[4:5]
	v_mov_b32_e32 v0, s4
.LBB0_420:
	s_or_b64 exec, exec, s[8:9]
	s_waitcnt vmcnt(0)

.LBB0_907:
	s_or_b64 exec, exec, s[4:5]
	s_mov_b64 s[4:5], exec
	v_mbcnt_lo_u32_b32 v0, s4, 0
	v_mbcnt_hi_u32_b32 v0, s5, v0
	v_cmp_eq_u32_e32 vcc, 0, v0
	s_waitcnt vmcnt(0)
	buffer_inv sc1
	s_and_saveexec_b64 s[8:9], vcc
	s_cbranch_execz .Ltramp_16
	s_bcnt1_i32_b64 s4, s[4:5]
	v_mov_b32_e32 v0, s4
	s_branch .Ltramp_16
